# P10 prompt q-tile loop: each key tile's LDS reads issued right after the previous tile's MFMAs (latency overlapped with mask/max VALU work)
# baseline (speedup 1.0000x reference)
.LBB0_1176:
	s_and_b32 s37, s34, 0x7ffffffe
	s_lshl_b32 s80, s37, 4
	v_or_b32_e32 v59, s80, v1
	s_add_i32 s36, s34, 1
	v_mad_u64_u32 v[64:65], s[34:35], v59, s3, v[30:31]
	ds_read_b128 v[60:63], v64
	ds_read_b128 v[68:71], v64 offset:64
	s_cmpk_gt_u32 s80, 0x7f
	v_add_u32_e32 v67, s66, v1
	s_cselect_b64 s[34:35], -1, 0
	s_or_b64 s[34:35], s[78:79], s[34:35]
	s_or_b32 s67, s66, 16
	s_waitcnt lgkmcnt(1)
	v_mfma_f32_16x16x32_bf16 v[60:63], v[60:63], v[14:17], 0
	v_add_u32_e32 v58, 0x80, v67
	s_waitcnt lgkmcnt(0)
	v_mfma_f32_16x16x32_bf16 v[62:65], v[68:71], v[10:13], v[60:63]
	s_add_i32 s88, s80, 16
	v_or_b32_e32 v144, s88, v1
	v_mad_u64_u32 v[144:145], s[90:91], v144, s3, v[30:31]
	ds_read_b128 v[148:151], v144
	ds_read_b128 v[152:155], v144 offset:64
	s_nop 4
	v_or_b32_e32 v60, s80, v32
	v_cmp_gt_u32_e32 vcc, v60, v67
	s_and_b64 vcc, vcc, s[34:35]
	v_or_b32_e32 v61, 2, v60
	v_cndmask_b32_e32 v59, v54, v62, vcc
	v_cmp_ge_u32_e32 vcc, v60, v67
	s_and_b64 vcc, vcc, s[34:35]
	v_or_b32_e32 v60, 3, v60
	v_cndmask_b32_e32 v62, v54, v63, vcc
	v_cmp_gt_u32_e32 vcc, v61, v67
	s_and_b64 vcc, vcc, s[34:35]
	v_max3_f32 v63, v59, s58, v62
	v_cndmask_b32_e32 v61, v54, v64, vcc
	v_cmp_gt_u32_e32 vcc, v60, v67
	s_and_b64 vcc, vcc, s[34:35]
	v_or_b32_e32 v64, s67, v1
	v_cndmask_b32_e32 v60, v54, v65, vcc
	s_waitcnt lgkmcnt(1)
	v_mfma_f32_16x16x32_bf16 v[68:71], v[148:151], v[14:17], 0
	v_max3_f32 v63, v63, v61, v60
	s_waitcnt lgkmcnt(0)
	v_mfma_f32_16x16x32_bf16 v[68:71], v[152:155], v[10:13], v[68:71]
	s_add_i32 s88, s80, 32
	v_or_b32_e32 v144, s88, v1
	v_mad_u64_u32 v[144:145], s[90:91], v144, s3, v[30:31]
	ds_read_b128 v[148:151], v144
	ds_read_b128 v[152:155], v144 offset:64
	v_or_b32_e32 v72, s67, v32
	v_cmp_gt_u32_e32 vcc, v72, v67
	v_cmp_le_u32_e64 s[34:35], v72, v58
	s_and_b64 s[34:35], vcc, s[34:35]
	s_and_b64 vcc, s[34:35], s[78:79]
	s_nop 2
	v_cndmask_b32_e32 v66, v54, v68, vcc
	v_cmp_ge_u32_e32 vcc, v72, v67
	v_cmp_lt_u32_e64 s[34:35], v72, v58
	s_and_b64 s[34:35], vcc, s[34:35]
	s_and_b64 vcc, s[34:35], s[78:79]
	v_cndmask_b32_e32 v65, v54, v69, vcc
	v_max3_f32 v68, v63, v66, v65
	v_or_b32_e32 v63, 2, v72
	v_cmp_gt_u32_e32 vcc, v63, v67
	v_cmp_le_u32_e64 s[34:35], v63, v58
	s_and_b64 s[34:35], vcc, s[34:35]
	s_and_b64 vcc, s[34:35], s[78:79]
	v_or_b32_e32 v63, 3, v72
	v_cndmask_b32_e32 v64, v54, v70, vcc
	v_cmp_gt_u32_e32 vcc, v63, v67
	v_cmp_le_u32_e64 s[34:35], v63, v58
	s_and_b64 s[34:35], vcc, s[34:35]
	s_and_b64 vcc, s[34:35], s[78:79]
	s_add_i32 s67, s37, 2
	v_cndmask_b32_e32 v63, v54, v71, vcc
	s_lshl_b32 s76, s67, 4
	v_max3_f32 v76, v68, v64, v63
	v_or_b32_e32 v68, s76, v1
	s_waitcnt lgkmcnt(1)
	v_mfma_f32_16x16x32_bf16 v[68:71], v[148:151], v[14:17], 0
	s_waitcnt lgkmcnt(0)
	v_mfma_f32_16x16x32_bf16 v[72:75], v[152:155], v[10:13], v[68:71]
	s_add_i32 s88, s80, 48
	v_or_b32_e32 v144, s88, v1
	v_mad_u64_u32 v[144:145], s[90:91], v144, s3, v[30:31]
	ds_read_b128 v[148:151], v144
	ds_read_b128 v[152:155], v144 offset:64
	s_nop 5
	v_or_b32_e32 v68, s76, v32
	v_cmp_gt_u32_e32 vcc, v68, v67
	v_cmp_le_u32_e64 s[34:35], v68, v58
	s_and_b64 s[34:35], vcc, s[34:35]
	s_cmpk_gt_u32 s76, 0x7f
	s_cselect_b64 s[76:77], -1, 0
	s_or_b64 s[76:77], s[78:79], s[76:77]
	s_and_b64 vcc, s[34:35], s[76:77]
	v_cndmask_b32_e32 v71, v54, v72, vcc
	v_cmp_ge_u32_e32 vcc, v68, v67
	v_cmp_lt_u32_e64 s[34:35], v68, v58
	s_and_b64 s[34:35], vcc, s[34:35]
	s_and_b64 vcc, s[34:35], s[76:77]
	v_or_b32_e32 v69, 2, v68
	v_cndmask_b32_e32 v70, v54, v73, vcc
	v_cmp_gt_u32_e32 vcc, v69, v67
	v_cmp_le_u32_e64 s[34:35], v69, v58
	s_and_b64 s[34:35], vcc, s[34:35]
	s_and_b64 vcc, s[34:35], s[76:77]
	v_or_b32_e32 v68, 3, v68
	v_cndmask_b32_e32 v69, v54, v74, vcc
	v_cmp_gt_u32_e32 vcc, v68, v67
	v_cmp_le_u32_e64 s[34:35], v68, v58
	s_and_b64 s[34:35], vcc, s[34:35]
	s_and_b64 vcc, s[34:35], s[76:77]
	v_max3_f32 v72, v76, v71, v70
	v_cndmask_b32_e32 v68, v54, v75, vcc
	s_add_i32 s76, s80, 48
	v_max3_f32 v80, v72, v69, v68
	v_or_b32_e32 v72, s76, v1
	s_waitcnt lgkmcnt(1)
	v_mfma_f32_16x16x32_bf16 v[72:75], v[148:151], v[14:17], 0
	s_waitcnt lgkmcnt(0)
	v_mfma_f32_16x16x32_bf16 v[76:79], v[152:155], v[10:13], v[72:75]
	s_add_i32 s88, s80, 64
	v_or_b32_e32 v144, s88, v1
	v_mad_u64_u32 v[144:145], s[90:91], v144, s3, v[30:31]
	ds_read_b128 v[148:151], v144
	ds_read_b128 v[152:155], v144 offset:64
	s_nop 5
	v_or_b32_e32 v72, s76, v32
	v_cmp_gt_u32_e32 vcc, v72, v67
	v_cmp_le_u32_e64 s[34:35], v72, v58
	s_and_b64 s[34:35], vcc, s[34:35]
	s_cmpk_gt_u32 s80, 0x4f
	s_cselect_b64 s[76:77], -1, 0
	s_or_b64 s[76:77], s[78:79], s[76:77]
	s_and_b64 vcc, s[34:35], s[76:77]
	v_cndmask_b32_e32 v75, v54, v76, vcc
	v_cmp_ge_u32_e32 vcc, v72, v67
	v_cmp_lt_u32_e64 s[34:35], v72, v58
	s_and_b64 s[34:35], vcc, s[34:35]
	s_and_b64 vcc, s[34:35], s[76:77]
	v_or_b32_e32 v73, 2, v72
	v_cndmask_b32_e32 v74, v54, v77, vcc
	v_cmp_gt_u32_e32 vcc, v73, v67
	v_cmp_le_u32_e64 s[34:35], v73, v58
	s_and_b64 s[34:35], vcc, s[34:35]
	s_and_b64 vcc, s[34:35], s[76:77]
	v_or_b32_e32 v72, 3, v72
	v_cndmask_b32_e32 v73, v54, v78, vcc
	v_cmp_gt_u32_e32 vcc, v72, v67
	v_cmp_le_u32_e64 s[34:35], v72, v58
	s_and_b64 s[34:35], vcc, s[34:35]
	s_and_b64 vcc, s[34:35], s[76:77]
	s_add_i32 s76, s37, 4
	v_max3_f32 v76, v80, v75, v74
	v_cndmask_b32_e32 v72, v54, v79, vcc
	s_lshl_b32 s77, s76, 4
	v_max3_f32 v84, v76, v73, v72
	v_or_b32_e32 v76, s77, v1
	s_waitcnt lgkmcnt(1)
	v_mfma_f32_16x16x32_bf16 v[76:79], v[148:151], v[14:17], 0
	s_waitcnt lgkmcnt(0)
	v_mfma_f32_16x16x32_bf16 v[80:83], v[152:155], v[10:13], v[76:79]
	s_add_i32 s88, s80, 80
	v_or_b32_e32 v144, s88, v1
	v_mad_u64_u32 v[144:145], s[90:91], v144, s3, v[30:31]
	ds_read_b128 v[148:151], v144
	ds_read_b128 v[152:155], v144 offset:64
	s_nop 5
	v_or_b32_e32 v76, s77, v32
	v_cmp_gt_u32_e32 vcc, v76, v67
	v_cmp_le_u32_e64 s[34:35], v76, v58
	s_and_b64 s[34:35], vcc, s[34:35]
	s_cmpk_gt_u32 s77, 0x7f
	s_cselect_b64 s[82:83], -1, 0
	s_or_b64 s[82:83], s[78:79], s[82:83]
	s_and_b64 vcc, s[34:35], s[82:83]
	v_cndmask_b32_e32 v79, v54, v80, vcc
	v_cmp_ge_u32_e32 vcc, v76, v67
	v_cmp_lt_u32_e64 s[34:35], v76, v58
	s_and_b64 s[34:35], vcc, s[34:35]
	s_and_b64 vcc, s[34:35], s[82:83]
	v_or_b32_e32 v77, 2, v76
	v_cndmask_b32_e32 v78, v54, v81, vcc
	v_cmp_gt_u32_e32 vcc, v77, v67
	v_cmp_le_u32_e64 s[34:35], v77, v58
	s_and_b64 s[34:35], vcc, s[34:35]
	s_and_b64 vcc, s[34:35], s[82:83]
	v_or_b32_e32 v76, 3, v76
	v_cndmask_b32_e32 v77, v54, v82, vcc
	v_cmp_gt_u32_e32 vcc, v76, v67
	v_cmp_le_u32_e64 s[34:35], v76, v58
	s_and_b64 s[34:35], vcc, s[34:35]
	s_and_b64 vcc, s[34:35], s[82:83]
	v_max3_f32 v80, v84, v79, v78
	v_cndmask_b32_e32 v76, v54, v83, vcc
	s_add_i32 s77, s80, 0x50
	v_max3_f32 v88, v80, v77, v76
	v_or_b32_e32 v80, s77, v1
	s_waitcnt lgkmcnt(1)
	v_mfma_f32_16x16x32_bf16 v[80:83], v[148:151], v[14:17], 0
	s_waitcnt lgkmcnt(0)
	v_mfma_f32_16x16x32_bf16 v[84:87], v[152:155], v[10:13], v[80:83]
	s_add_i32 s88, s80, 96
	v_or_b32_e32 v144, s88, v1
	v_mad_u64_u32 v[144:145], s[90:91], v144, s3, v[30:31]
	ds_read_b128 v[148:151], v144
	ds_read_b128 v[152:155], v144 offset:64
	s_nop 5
	v_or_b32_e32 v80, s77, v32
	v_cmp_gt_u32_e32 vcc, v80, v67
	v_cmp_le_u32_e64 s[34:35], v80, v58
	s_and_b64 s[34:35], vcc, s[34:35]
	s_cmp_gt_u32 s80, 47
	s_cselect_b64 s[82:83], -1, 0
	s_or_b64 s[82:83], s[78:79], s[82:83]
	s_and_b64 vcc, s[34:35], s[82:83]
	v_cndmask_b32_e32 v83, v54, v84, vcc
	v_cmp_ge_u32_e32 vcc, v80, v67
	v_cmp_lt_u32_e64 s[34:35], v80, v58
	s_and_b64 s[34:35], vcc, s[34:35]
	s_and_b64 vcc, s[34:35], s[82:83]
	v_or_b32_e32 v81, 2, v80
	v_cndmask_b32_e32 v82, v54, v85, vcc
	v_cmp_gt_u32_e32 vcc, v81, v67
	v_cmp_le_u32_e64 s[34:35], v81, v58
	s_and_b64 s[34:35], vcc, s[34:35]
	s_and_b64 vcc, s[34:35], s[82:83]
	v_or_b32_e32 v80, 3, v80
	v_cndmask_b32_e32 v81, v54, v86, vcc
	v_cmp_gt_u32_e32 vcc, v80, v67
	v_cmp_le_u32_e64 s[34:35], v80, v58
	s_and_b64 s[34:35], vcc, s[34:35]
	s_and_b64 vcc, s[34:35], s[82:83]
	s_add_i32 s77, s37, 6
	v_max3_f32 v84, v88, v83, v82
	v_cndmask_b32_e32 v80, v54, v87, vcc
	s_lshl_b32 s81, s77, 4
	v_max3_f32 v92, v84, v81, v80
	v_or_b32_e32 v84, s81, v1
	s_waitcnt lgkmcnt(1)
	v_mfma_f32_16x16x32_bf16 v[84:87], v[148:151], v[14:17], 0
	s_waitcnt lgkmcnt(0)
	v_mfma_f32_16x16x32_bf16 v[88:91], v[152:155], v[10:13], v[84:87]
	s_add_i32 s88, s80, 112
	v_or_b32_e32 v144, s88, v1
	v_mad_u64_u32 v[144:145], s[90:91], v144, s3, v[30:31]
	ds_read_b128 v[148:151], v144
	ds_read_b128 v[152:155], v144 offset:64
	s_nop 5
	v_or_b32_e32 v84, s81, v32
	v_cmp_gt_u32_e32 vcc, v84, v67
	v_cmp_le_u32_e64 s[34:35], v84, v58
	s_and_b64 s[34:35], vcc, s[34:35]
	s_cmpk_gt_u32 s81, 0x7f
	s_cselect_b64 s[82:83], -1, 0
	s_or_b64 s[82:83], s[78:79], s[82:83]
	s_and_b64 vcc, s[34:35], s[82:83]
	v_cndmask_b32_e32 v87, v54, v88, vcc
	v_cmp_ge_u32_e32 vcc, v84, v67
	v_cmp_lt_u32_e64 s[34:35], v84, v58
	s_and_b64 s[34:35], vcc, s[34:35]
	s_and_b64 vcc, s[34:35], s[82:83]
	v_or_b32_e32 v85, 2, v84
	v_cndmask_b32_e32 v86, v54, v89, vcc
	v_cmp_gt_u32_e32 vcc, v85, v67
	v_cmp_le_u32_e64 s[34:35], v85, v58
	s_and_b64 s[34:35], vcc, s[34:35]
	s_and_b64 vcc, s[34:35], s[82:83]
	v_or_b32_e32 v84, 3, v84
	v_cndmask_b32_e32 v85, v54, v90, vcc
	v_cmp_gt_u32_e32 vcc, v84, v67
	v_cmp_le_u32_e64 s[34:35], v84, v58
	s_and_b64 s[34:35], vcc, s[34:35]
	s_and_b64 vcc, s[34:35], s[82:83]
	v_max3_f32 v88, v92, v87, v86
	v_cndmask_b32_e32 v84, v54, v91, vcc
	s_add_i32 s81, s80, 0x70
	v_max3_f32 v96, v88, v85, v84
	v_or_b32_e32 v88, s81, v1
	s_waitcnt lgkmcnt(1)
	v_mfma_f32_16x16x32_bf16 v[88:91], v[148:151], v[14:17], 0
	s_waitcnt lgkmcnt(0)
	v_mfma_f32_16x16x32_bf16 v[90:93], v[152:155], v[10:13], v[88:91]
	s_add_i32 s88, s80, 128
	v_or_b32_e32 v144, s88, v1
	v_mad_u64_u32 v[144:145], s[90:91], v144, s3, v[30:31]
	ds_read_b128 v[148:151], v144
	ds_read_b128 v[152:155], v144 offset:64
	s_nop 5
	v_or_b32_e32 v88, s81, v32
	v_cmp_gt_u32_e32 vcc, v88, v67
	v_cmp_le_u32_e64 s[34:35], v88, v58
	s_and_b64 s[34:35], vcc, s[34:35]
	s_or_b32 s81, s37, s61
	s_cmp_lg_u32 s81, 0
	s_cselect_b64 s[82:83], -1, 0
	s_and_b64 vcc, s[82:83], s[34:35]
	v_cndmask_b32_e32 v100, v54, v90, vcc
	v_cmp_ge_u32_e32 vcc, v88, v67
	v_cmp_lt_u32_e64 s[34:35], v88, v58
	s_and_b64 s[34:35], vcc, s[34:35]
	s_and_b64 vcc, s[82:83], s[34:35]
	v_or_b32_e32 v89, 2, v88
	v_cndmask_b32_e32 v90, v54, v91, vcc
	v_cmp_gt_u32_e32 vcc, v89, v67
	v_cmp_le_u32_e64 s[34:35], v89, v58
	s_and_b64 s[34:35], vcc, s[34:35]
	s_and_b64 vcc, s[82:83], s[34:35]
	v_or_b32_e32 v88, 3, v88
	v_cndmask_b32_e32 v89, v54, v92, vcc
	v_cmp_gt_u32_e32 vcc, v88, v67
	v_cmp_le_u32_e64 s[34:35], v88, v58
	s_and_b64 s[34:35], vcc, s[34:35]
	s_and_b64 vcc, s[82:83], s[34:35]
	s_add_i32 s34, s37, 8
	v_max3_f32 v91, v96, v100, v90
	v_cndmask_b32_e32 v88, v54, v93, vcc
	s_lshl_b32 s35, s34, 4
	v_max3_f32 v67, v91, v89, v88
	v_or_b32_e32 v91, s35, v1
	s_waitcnt lgkmcnt(1)
	v_mfma_f32_16x16x32_bf16 v[92:95], v[148:151], v[14:17], 0
	v_or_b32_e32 v91, s35, v32
	v_cmp_le_u32_e32 vcc, v91, v58
	s_add_i32 s35, s80, 0x90
	s_waitcnt lgkmcnt(0)
	v_mfma_f32_16x16x32_bf16 v[92:95], v[152:155], v[10:13], v[92:95]
	s_add_i32 s66, s66, 16
	s_cmp_eq_u32 s36, 8
	s_nop 5
	v_cndmask_b32_e32 v98, v54, v92, vcc
	v_cmp_lt_u32_e32 vcc, v91, v58
	v_or_b32_e32 v92, 2, v91
	v_or_b32_e32 v91, 3, v91
	v_cndmask_b32_e32 v99, v54, v93, vcc
	v_cmp_le_u32_e32 vcc, v92, v58
	v_or_b32_e32 v92, s35, v1
	v_mad_u64_u32 v[96:97], s[80:81], v92, s3, v[30:31]
	v_cndmask_b32_e32 v101, v54, v94, vcc
	v_cmp_le_u32_e32 vcc, v91, v58
	v_max3_f32 v67, v67, v98, v99
	s_nop 0
	v_cndmask_b32_e32 v91, v54, v95, vcc
	ds_read_b128 v[92:95], v96
	s_waitcnt lgkmcnt(0)
	v_mfma_f32_16x16x32_bf16 v[14:17], v[92:95], v[14:17], 0
	ds_read_b128 v[92:95], v96 offset:64
	v_max3_f32 v67, v67, v101, v91
	s_waitcnt lgkmcnt(0)
	v_mfma_f32_16x16x32_bf16 v[10:13], v[92:95], v[10:13], v[14:17]
	s_nop 3
	v_or_b32_e32 v14, s35, v32
	v_cmp_le_u32_e32 vcc, v14, v58
	v_or_b32_e32 v15, 2, v14
	s_nop 0
	v_cndmask_b32_e32 v17, v54, v10, vcc
	v_cmp_lt_u32_e32 vcc, v14, v58
	v_or_b32_e32 v14, 3, v14
	s_nop 0
	v_cndmask_b32_e32 v11, v54, v11, vcc
	v_cmp_le_u32_e32 vcc, v15, v58
	v_max3_f32 v10, v67, v17, v11
	s_nop 0
	v_cndmask_b32_e32 v12, v54, v12, vcc
	v_cmp_le_u32_e32 vcc, v14, v58
	s_nop 1
	v_cndmask_b32_e32 v92, v54, v13, vcc
	v_max3_f32 v10, v10, v12, v92
	ds_bpermute_b32 v13, v55, v10
	s_waitcnt lgkmcnt(0)
	v_max_f32_e32 v13, v13, v13
	v_max_f32_e32 v10, v10, v13
	ds_bpermute_b32 v13, v56, v10
	s_waitcnt vmcnt(0) lgkmcnt(0)
	v_max3_f32 v10, v10, v13, v37
	v_sub_f32_e32 v14, v62, v10
	v_mul_f32_e32 v14, 0x3fb8aa3b, v14
	v_exp_f32_e32 v94, v14
	v_sub_f32_e32 v14, v61, v10
	v_mul_f32_e32 v14, 0x3fb8aa3b, v14
	v_exp_f32_e32 v95, v14
	v_sub_f32_e32 v14, v60, v10
	v_mul_f32_e32 v14, 0x3fb8aa3b, v14
	v_exp_f32_e32 v96, v14
	v_sub_f32_e32 v14, v66, v10
	v_mul_f32_e32 v14, 0x3fb8aa3b, v14
	v_exp_f32_e32 v97, v14
	v_sub_f32_e32 v14, v65, v10
	v_mul_f32_e32 v14, 0x3fb8aa3b, v14
	v_exp_f32_e32 v102, v14
	v_sub_f32_e32 v14, v64, v10
	v_mul_f32_e32 v14, 0x3fb8aa3b, v14
	v_exp_f32_e32 v103, v14
	v_sub_f32_e32 v14, v63, v10
	v_mul_f32_e32 v14, 0x3fb8aa3b, v14
	v_exp_f32_e32 v104, v14
	v_sub_f32_e32 v14, v71, v10
	v_mul_f32_e32 v14, 0x3fb8aa3b, v14
	v_exp_f32_e32 v105, v14
	v_sub_f32_e32 v14, v70, v10
	v_mul_f32_e32 v14, 0x3fb8aa3b, v14
	v_exp_f32_e32 v106, v14
	v_sub_f32_e32 v14, v69, v10
	v_mul_f32_e32 v14, 0x3fb8aa3b, v14
	v_exp_f32_e32 v107, v14
	v_sub_f32_e32 v14, v68, v10
	v_mul_f32_e32 v14, 0x3fb8aa3b, v14
	v_exp_f32_e32 v108, v14
	v_sub_f32_e32 v14, v75, v10
	v_mul_f32_e32 v14, 0x3fb8aa3b, v14
	v_exp_f32_e32 v109, v14
	v_sub_f32_e32 v14, v74, v10
	v_mul_f32_e32 v14, 0x3fb8aa3b, v14
	v_exp_f32_e32 v110, v14
	v_sub_f32_e32 v14, v73, v10
	v_mul_f32_e32 v14, 0x3fb8aa3b, v14
	v_exp_f32_e32 v111, v14
	v_sub_f32_e32 v14, v72, v10
	v_sub_f32_e32 v13, v59, v10
	v_mul_f32_e32 v14, 0x3fb8aa3b, v14
	v_mul_f32_e32 v13, 0x3fb8aa3b, v13
	v_exp_f32_e32 v112, v14
	v_sub_f32_e32 v14, v79, v10
	v_exp_f32_e32 v93, v13
	v_mul_f32_e32 v14, 0x3fb8aa3b, v14
	v_exp_f32_e32 v66, v14
	v_sub_f32_e32 v14, v78, v10
	v_mul_f32_e32 v14, 0x3fb8aa3b, v14
	v_exp_f32_e32 v69, v14
	v_sub_f32_e32 v14, v77, v10
	v_add_f32_e32 v13, 0, v93
	v_mul_f32_e32 v14, 0x3fb8aa3b, v14
	v_add_f32_e32 v13, v94, v13
	v_exp_f32_e32 v71, v14
	v_sub_f32_e32 v14, v76, v10
	v_add_f32_e32 v13, v95, v13
	v_mul_f32_e32 v14, 0x3fb8aa3b, v14
	v_add_f32_e32 v13, v96, v13
	v_exp_f32_e32 v72, v14
	v_sub_f32_e32 v14, v83, v10
	v_add_f32_e32 v13, v97, v13
	v_mul_f32_e32 v14, 0x3fb8aa3b, v14
	v_add_f32_e32 v13, v102, v13
	v_exp_f32_e32 v73, v14
	v_sub_f32_e32 v14, v82, v10
	v_add_f32_e32 v13, v103, v13
	v_mul_f32_e32 v14, 0x3fb8aa3b, v14
	v_add_f32_e32 v13, v104, v13
	v_exp_f32_e32 v113, v14
	v_sub_f32_e32 v14, v81, v10
	v_add_f32_e32 v13, v105, v13
	v_mul_f32_e32 v14, 0x3fb8aa3b, v14
	v_add_f32_e32 v13, v106, v13
	v_exp_f32_e32 v114, v14
	v_sub_f32_e32 v14, v80, v10
	v_add_f32_e32 v13, v107, v13
	v_mul_f32_e32 v14, 0x3fb8aa3b, v14
	v_add_f32_e32 v13, v108, v13
	v_exp_f32_e32 v115, v14
	v_sub_f32_e32 v14, v87, v10
	v_add_f32_e32 v13, v109, v13
	v_mul_f32_e32 v14, 0x3fb8aa3b, v14
	v_add_f32_e32 v13, v110, v13
	v_exp_f32_e32 v61, v14
	v_sub_f32_e32 v14, v86, v10
	v_add_f32_e32 v13, v111, v13
	v_mul_f32_e32 v14, 0x3fb8aa3b, v14
	v_add_f32_e32 v13, v112, v13
	v_exp_f32_e32 v62, v14
	v_sub_f32_e32 v14, v85, v10
	v_add_f32_e32 v13, v66, v13
	v_mul_f32_e32 v14, 0x3fb8aa3b, v14
	v_add_f32_e32 v13, v69, v13
	v_exp_f32_e32 v63, v14
	v_sub_f32_e32 v14, v84, v10
	v_add_f32_e32 v13, v71, v13
	v_mul_f32_e32 v14, 0x3fb8aa3b, v14
	v_add_f32_e32 v13, v72, v13
	v_exp_f32_e32 v64, v14
	v_sub_f32_e32 v14, v100, v10
	v_add_f32_e32 v13, v73, v13
	v_mul_f32_e32 v14, 0x3fb8aa3b, v14
	v_add_f32_e32 v13, v113, v13
	v_exp_f32_e32 v65, v14
	v_sub_f32_e32 v14, v90, v10
	v_add_f32_e32 v13, v114, v13
	v_mul_f32_e32 v14, 0x3fb8aa3b, v14
	v_add_f32_e32 v13, v115, v13
	v_exp_f32_e32 v67, v14
	v_sub_f32_e32 v14, v89, v10
	v_add_f32_e32 v13, v61, v13
	v_mul_f32_e32 v14, 0x3fb8aa3b, v14
	v_add_f32_e32 v13, v62, v13
	v_exp_f32_e32 v68, v14
	v_sub_f32_e32 v14, v88, v10
	v_add_f32_e32 v13, v63, v13
	v_mul_f32_e32 v14, 0x3fb8aa3b, v14
	v_add_f32_e32 v13, v64, v13
	v_exp_f32_e32 v70, v14
	v_add_f32_e32 v13, v65, v13
	v_add_f32_e32 v13, v67, v13
	v_add_f32_e32 v13, v68, v13
	v_add_f32_e32 v14, v70, v13
	v_sub_f32_e32 v13, v98, v10
	v_mul_f32_e32 v13, 0x3fb8aa3b, v13
	v_exp_f32_e32 v13, v13
	v_sub_f32_e32 v17, v17, v10
	v_mul_f32_e32 v17, 0x3fb8aa3b, v17
	v_exp_f32_e32 v17, v17
	v_add_f32_e32 v15, v13, v14
	v_sub_f32_e32 v14, v99, v10
	v_mul_f32_e32 v14, 0x3fb8aa3b, v14
	v_exp_f32_e32 v14, v14
	v_sub_f32_e32 v11, v11, v10
	v_mul_f32_e32 v11, 0x3fb8aa3b, v11
	v_lshl_add_u32 v90, s37, 5, v49
	v_add_f32_e32 v16, v14, v15
	v_sub_f32_e32 v15, v101, v10
	v_mul_f32_e32 v15, 0x3fb8aa3b, v15
	v_exp_f32_e32 v15, v15
	v_add_u32_e32 v78, 0x9000, v90
	ds_read2_b64 v[78:81], v78 offset1:4
	v_sub_f32_e32 v12, v12, v10
	v_add_f32_e32 v58, v15, v16
	v_sub_f32_e32 v16, v91, v10
	v_mul_f32_e32 v16, 0x3fb8aa3b, v16
	v_exp_f32_e32 v16, v16
	v_mul_f32_e32 v12, 0x3fb8aa3b, v12
	v_add_u32_e32 v82, 0xb000, v90
	v_add_u32_e32 v86, 0xd000, v90
	v_add_f32_e32 v58, v16, v58
	v_add_f32_e32 v59, v17, v58
	v_exp_f32_e32 v58, v11
	v_add_u32_e32 v90, 0xf000, v90
	v_lshl_add_u32 v98, s67, 5, v49
	v_cvt_pk_bf16_f32 v74, v93, v94
	v_add_f32_e32 v11, v58, v59
	v_exp_f32_e32 v59, v12
	v_sub_f32_e32 v12, v92, v10
	ds_read2_b64 v[82:85], v82 offset0:32 offset1:36
	ds_read2_b64 v[86:89], v86 offset0:64 offset1:68
	ds_read2_b64 v[90:93], v90 offset0:96 offset1:100
	v_add_u32_e32 v94, 0x9000, v98
	v_cvt_pk_bf16_f32 v75, v95, v96
	v_cvt_pk_bf16_f32 v76, v97, v102
	ds_read2_b64 v[94:97], v94 offset1:4
	v_cvt_pk_bf16_f32 v77, v103, v104
	v_cvt_pk_bf16_f32 v62, v61, v62
	v_lshl_add_u32 v61, s77, 5, v49
	s_waitcnt lgkmcnt(4)
	v_mfma_f32_16x16x32_bf16 v[78:81], v[78:81], v[74:77], 0
	v_cvt_pk_bf16_f32 v63, v63, v64
	v_cvt_pk_bf16_f32 v64, v65, v67
	v_cvt_pk_bf16_f32 v65, v68, v70
	s_waitcnt lgkmcnt(3)
	v_mfma_f32_16x16x32_bf16 v[82:85], v[82:85], v[74:77], 0
	v_add_u32_e32 v70, 0xb000, v61
	v_mul_f32_e32 v12, 0x3fb8aa3b, v12
	v_exp_f32_e32 v60, v12
	s_waitcnt lgkmcnt(2)
	v_mfma_f32_16x16x32_bf16 v[86:89], v[86:89], v[74:77], 0
	v_cvt_pk_bf16_f32 v14, v13, v14
	v_lshl_add_u32 v13, s34, 5, v49
	v_add_f32_e32 v11, v59, v11
	s_waitcnt lgkmcnt(1)
	v_mfma_f32_16x16x32_bf16 v[74:77], v[90:93], v[74:77], 0
	v_cvt_pk_bf16_f32 v90, v105, v106
	v_cvt_pk_bf16_f32 v91, v107, v108
	v_cvt_pk_bf16_f32 v92, v109, v110
	v_cvt_pk_bf16_f32 v93, v111, v112
	v_cvt_pk_bf16_f32 v15, v15, v16
	v_cvt_pk_bf16_f32 v16, v17, v58
	s_waitcnt lgkmcnt(0)
	v_mfma_f32_16x16x32_bf16 v[78:81], v[94:97], v[90:93], v[78:81]
	v_add_u32_e32 v94, 0xb000, v98
	ds_read2_b64 v[94:97], v94 offset0:32 offset1:36
	v_add_u32_e32 v58, 0x9000, v13
	s_waitcnt lgkmcnt(0)
	v_mfma_f32_16x16x32_bf16 v[82:85], v[94:97], v[90:93], v[82:85]
	v_add_u32_e32 v94, 0xd000, v98
	ds_read2_b64 v[94:97], v94 offset0:64 offset1:68
	v_add_f32_e32 v11, v60, v11
	s_waitcnt lgkmcnt(0)
	v_mfma_f32_16x16x32_bf16 v[86:89], v[94:97], v[90:93], v[86:89]
	v_add_u32_e32 v94, 0xf000, v98
	ds_read2_b64 v[94:97], v94 offset0:96 offset1:100
	v_cvt_pk_bf16_f32 v17, v59, v60
	s_waitcnt lgkmcnt(0)
	v_mfma_f32_16x16x32_bf16 v[74:77], v[94:97], v[90:93], v[74:77]
	v_cvt_pk_bf16_f32 v90, v66, v69
	v_lshl_add_u32 v66, s76, 5, v49
	v_add_u32_e32 v69, 0x9000, v66
	ds_read2_b64 v[94:97], v69 offset1:4
	v_cvt_pk_bf16_f32 v91, v71, v72
	v_cvt_pk_bf16_f32 v92, v73, v113
	v_cvt_pk_bf16_f32 v93, v114, v115
	v_add_u32_e32 v69, 0xb000, v66
	ds_bpermute_b32 v12, v55, v11
	s_waitcnt lgkmcnt(1)
	v_mfma_f32_16x16x32_bf16 v[78:81], v[94:97], v[90:93], v[78:81]
	ds_read2_b64 v[94:97], v69 offset0:32 offset1:36
	v_add_u32_e32 v69, 0xd000, v66
	v_add_u32_e32 v66, 0xf000, v66
	s_waitcnt lgkmcnt(0)
	v_mfma_f32_16x16x32_bf16 v[82:85], v[94:97], v[90:93], v[82:85]
	ds_read2_b64 v[94:97], v69 offset0:64 offset1:68
	v_add_f32_e32 v11, v11, v12
	ds_bpermute_b32 v12, v56, v11
	s_waitcnt lgkmcnt(1)
	v_mfma_f32_16x16x32_bf16 v[86:89], v[94:97], v[90:93], v[86:89]
	ds_read2_b64 v[94:97], v66 offset0:96 offset1:100
	v_add_u32_e32 v66, 0x9000, v61
	ds_read2_b64 v[66:69], v66 offset1:4
	s_waitcnt lgkmcnt(1)
	v_mfma_f32_16x16x32_bf16 v[72:75], v[94:97], v[90:93], v[74:77]
	v_sub_f32_e32 v10, v37, v10
	v_mul_f32_e32 v10, 0x3fb8aa3b, v10
	v_exp_f32_e32 v10, v10
	s_waitcnt lgkmcnt(0)
	v_mfma_f32_16x16x32_bf16 v[66:69], v[66:69], v[62:65], v[78:81]
	v_add_f32_e32 v11, v11, v12
	v_add_f32_e32 v10, v10, v11
	s_nop 0
	ds_read2_b64 v[76:79], v70 offset0:32 offset1:36
	v_add_u32_e32 v70, 0xd000, v61
	s_waitcnt lgkmcnt(0)
	v_mfma_f32_16x16x32_bf16 v[76:79], v[76:79], v[62:65], v[82:85]
	s_nop 2
	ds_read2_b64 v[80:83], v70 offset0:64 offset1:68
	v_add_u32_e32 v61, 0xf000, v61
	v_add_u32_e32 v70, 0xd000, v13
	s_waitcnt lgkmcnt(0)
	v_mfma_f32_16x16x32_bf16 v[80:83], v[80:83], v[62:65], v[86:89]
	s_nop 2
	ds_read2_b64 v[84:87], v61 offset0:96 offset1:100
	ds_read2_b64 v[58:61], v58 offset1:4
	v_div_scale_f32 v11, s[34:35], v10, v10, 1.0
	s_waitcnt lgkmcnt(0)
	v_mfma_f32_16x16x32_bf16 v[58:61], v[58:61], v[14:17], v[66:69]
	s_nop 2
	v_add_u32_e32 v66, 0xb000, v13
	ds_read2_b64 v[66:69], v66 offset0:32 offset1:36
	v_add_u32_e32 v13, 0xf000, v13
	v_mfma_f32_16x16x32_bf16 v[62:65], v[84:87], v[62:65], v[72:75]
	v_rcp_f32_e32 v12, v11
	s_mov_b32 s34, s36
	s_waitcnt lgkmcnt(0)
	v_mfma_f32_16x16x32_bf16 v[66:69], v[66:69], v[14:17], v[76:79]
	ds_read2_b64 v[70:73], v70 offset0:64 offset1:68
	s_nop 1
	ds_read2_b64 v[74:77], v13 offset0:96 offset1:100
	v_fma_f32 v13, -v11, v12, 1.0
	v_fmac_f32_e32 v12, v13, v12
	v_div_scale_f32 v13, vcc, 1.0, v10, 1.0
	s_waitcnt lgkmcnt(1)
	v_mfma_f32_16x16x32_bf16 v[70:73], v[70:73], v[14:17], v[80:83]
	s_waitcnt lgkmcnt(0)
	v_mfma_f32_16x16x32_bf16 v[14:17], v[74:77], v[14:17], v[62:65]
	s_nop 2
	v_mul_f32_e32 v62, v13, v12
	v_fma_f32 v63, -v11, v62, v13
	v_fmac_f32_e32 v62, v63, v12
	v_fma_f32 v11, -v11, v62, v13
	v_div_fmas_f32 v11, v11, v12, v62
	v_div_fixup_f32 v10, v11, v10, 1.0
	v_pk_mul_f32 v[12:13], v[60:61], v[10:11] op_sel_hi:[1,0]
	v_pk_mul_f32 v[58:59], v[58:59], v[10:11] op_sel_hi:[1,0]
	v_pk_mul_f32 v[16:17], v[10:11], v[16:17] op_sel_hi:[0,1]
	v_cvt_pk_bf16_f32 v58, v58, v59
	v_cvt_pk_bf16_f32 v59, v12, v13
	v_lshl_add_u64 v[12:13], v[38:39], 0, v[40:41]
	global_store_dwordx2 v[12:13], v[58:59], off
	v_pk_mul_f32 v[40:41], v[10:11], v[68:69] op_sel_hi:[0,1]
	v_pk_mul_f32 v[58:59], v[10:11], v[66:67] op_sel_hi:[0,1]
	v_cvt_pk_bf16_f32 v58, v58, v59
	v_cvt_pk_bf16_f32 v59, v40, v41
	global_store_dwordx2 v[12:13], v[58:59], off offset:32
	v_pk_mul_f32 v[40:41], v[10:11], v[72:73] op_sel_hi:[0,1]
	v_pk_mul_f32 v[58:59], v[10:11], v[70:71] op_sel_hi:[0,1]
	v_pk_mul_f32 v[10:11], v[10:11], v[14:15] op_sel_hi:[0,1]
	v_cvt_pk_bf16_f32 v58, v58, v59
	v_cvt_pk_bf16_f32 v59, v40, v41
	v_cvt_pk_bf16_f32 v10, v10, v11
	v_cvt_pk_bf16_f32 v11, v16, v17
	global_store_dwordx2 v[12:13], v[58:59], off offset:64
	global_store_dwordx2 v[12:13], v[10:11], off offset:96
	v_mov_b64_e32 v[16:17], v[8:9]
	v_mov_b64_e32 v[12:13], v[4:5]
	v_mov_b64_e32 v[14:15], v[6:7]
	v_mov_b64_e32 v[10:11], v[2:3]
	s_cbranch_scc1 .LBB0_1112
